# V5 + FILL_ROW_SCALES (phases 3, 9): row-scale table loads of all iterations issued back to back, one wait, then the reductions
# baseline (speedup 1.0000x reference)
.LBB0_550:
	s_or_b64 exec, exec, s[2:3]
	s_abs_i32 s0, s66
	v_cvt_f32_u32_e32 v1, s0
	s_sub_i32 s1, s66, s33
	s_add_i32 s2, s1, 0x9ff
	s_sub_i32 s1, 0xfffff601, s1
	v_rcp_iflag_f32_e32 v1, v1
	s_xor_b32 s4, s2, s66
	s_sub_i32 s3, 0, s0
	s_max_i32 s1, s2, s1
	v_mul_f32_e32 v1, 0x4f7ffffe, v1
	v_cvt_u32_f32_e32 v1, v1
	s_ashr_i32 s2, s4, 31
	v_mov_b32_e32 v0, v8
	v_readfirstlane_b32 s4, v1
	s_mul_i32 s3, s3, s4
	s_mul_hi_u32 s3, s4, s3
	s_add_i32 s4, s4, s3
	s_mul_hi_u32 s3, s1, s4
	s_mul_i32 s4, s3, s0
	s_sub_i32 s1, s1, s4
	s_add_i32 s4, s3, 1
	s_sub_i32 s5, s1, s0
	s_cmp_ge_u32 s1, s0
	s_cselect_b32 s3, s4, s3
	s_cselect_b32 s1, s5, s1
	s_add_i32 s4, s3, 1
	s_cmp_ge_u32 s1, s0
	s_cselect_b32 s0, s4, s3
	s_xor_b32 s0, s0, s2
	s_sub_i32 s0, s0, s2
	s_lshl_b32 s0, s0, 8
	v_cmp_gt_i32_e32 vcc, s0, v0
	s_and_saveexec_b64 s[2:3], vcc
	s_cbranch_execz .LBB0_553
	s_add_u32 s4, s40, 0x3400000
	v_lshl_add_u32 v2, v0, 2, 0
	s_addc_u32 s5, s41, 0
	v_and_b32_e32 v1, 0xff, v0
	v_add_u32_e32 v2, 0x20100, v2
	s_mov_b64 s[6:7], 0
	v_mov_b32_e32 v3, 0x140
	v_mov_b32_e32 v4, 0x141
	s_mov_b32 s1, 0x66666667
	s_movk_i32 s10, 0xa0
	v_mov_b32_e32 v5, 0x358637bd
	s_mov_b64 s[14:15], 0
	s_mov_b64 s[16:17], 0
	s_mov_b64 s[22:23], 0
	s_mov_b64 s[24:25], 0
	s_mov_b64 s[26:27], 0
	s_mov_b64 s[98:99], 0
	v_mov_b32_e32 v122, v2
	s_mov_b64 s[14:15], exec
	v_ashrrev_i32_e32 v6, 8, v0
	v_mul_lo_u32 v6, v6, s66
	v_add_u32_e32 v7, s33, v6
	v_ashrrev_i32_e32 v6, 31, v7
	v_lshrrev_b32_e32 v6, 29, v6
	v_add_u32_e32 v9, v7, v6
	v_ashrrev_i32_e32 v6, 3, v9
	v_and_b32_e32 v9, -8, v9
	v_sub_u32_e32 v7, v7, v9
	v_cmp_gt_i32_e32 vcc, 0, v7
	v_add_u32_e32 v0, 0x200, v0
	s_nop 0
	v_cndmask_b32_e32 v9, v3, v4, vcc
	v_mad_u64_u32 v[6:7], s[12:13], v7, v9, v[6:7]
	v_mul_hi_i32 v7, v6, s1
	v_lshrrev_b32_e32 v9, 31, v7
	v_ashrrev_i32_e32 v7, 6, v7
	v_add_u32_e32 v7, v7, v9
	v_lshlrev_b32_e32 v9, 3, v7
	v_mul_lo_u32 v7, v7, s10
	v_sub_u32_e32 v10, 0x80, v9
	v_sub_u32_e32 v6, v6, v7
	v_min_i32_e32 v7, 8, v10
	v_sub_u32_e32 v11, 0, v6
	v_ashrrev_i32_e32 v10, 31, v6
	v_max_i32_e32 v6, v6, v11
	v_sub_u32_e32 v11, 0, v7
	v_max_i32_e32 v7, v7, v11
	v_cvt_f32_u32_e32 v11, v7
	v_sub_u32_e32 v12, 0, v7
	v_rcp_iflag_f32_e32 v11, v11
	s_nop 0
	v_mul_f32_e32 v11, 0x4f7ffffe, v11
	v_cvt_u32_f32_e32 v11, v11
	v_mul_lo_u32 v12, v12, v11
	v_mul_hi_u32 v12, v11, v12
	v_add_u32_e32 v11, v11, v12
	v_mul_hi_u32 v11, v6, v11
	v_mul_lo_u32 v11, v11, v7
	v_sub_u32_e32 v6, v6, v11
	v_sub_u32_e32 v11, v6, v7
	v_cmp_ge_u32_e32 vcc, v6, v7
	s_nop 1
	v_cndmask_b32_e32 v6, v6, v11, vcc
	v_sub_u32_e32 v11, v6, v7
	v_cmp_ge_u32_e32 vcc, v6, v7
	s_nop 1
	v_cndmask_b32_e32 v6, v6, v11, vcc
	v_xor_b32_e32 v6, v6, v10
	v_sub_u32_e32 v6, v6, v10
	v_add_u32_e32 v6, v9, v6
	v_lshl_or_b32 v6, v6, 8, v1
	v_ashrrev_i32_e32 v7, 31, v6
	v_lshlrev_b64 v[6:7], 6, v[6:7]
	v_lshl_add_u64 v[6:7], s[4:5], 0, v[6:7]
	global_load_dwordx4 v[26:29], v[6:7], off
	global_load_dwordx4 v[30:33], v[6:7], off offset:32
	global_load_dwordx4 v[34:37], v[6:7], off offset:16
	global_load_dwordx4 v[38:41], v[6:7], off offset:48
	v_cmp_le_i32_e32 vcc, s0, v0
	s_or_b64 s[6:7], vcc, s[6:7]
	s_andn2_b64 exec, exec, s[6:7]
	s_cbranch_execz .Lfrs_wait_p3
	s_mov_b64 s[16:17], exec
	v_ashrrev_i32_e32 v6, 8, v0
	v_mul_lo_u32 v6, v6, s66
	v_add_u32_e32 v7, s33, v6
	v_ashrrev_i32_e32 v6, 31, v7
	v_lshrrev_b32_e32 v6, 29, v6
	v_add_u32_e32 v9, v7, v6
	v_ashrrev_i32_e32 v6, 3, v9
	v_and_b32_e32 v9, -8, v9
	v_sub_u32_e32 v7, v7, v9
	v_cmp_gt_i32_e32 vcc, 0, v7
	v_add_u32_e32 v0, 0x200, v0
	s_nop 0
	v_cndmask_b32_e32 v9, v3, v4, vcc
	v_mad_u64_u32 v[6:7], s[12:13], v7, v9, v[6:7]
	v_mul_hi_i32 v7, v6, s1
	v_lshrrev_b32_e32 v9, 31, v7
	v_ashrrev_i32_e32 v7, 6, v7
	v_add_u32_e32 v7, v7, v9
	v_lshlrev_b32_e32 v9, 3, v7
	v_mul_lo_u32 v7, v7, s10
	v_sub_u32_e32 v10, 0x80, v9
	v_sub_u32_e32 v6, v6, v7
	v_min_i32_e32 v7, 8, v10
	v_sub_u32_e32 v11, 0, v6
	v_ashrrev_i32_e32 v10, 31, v6
	v_max_i32_e32 v6, v6, v11
	v_sub_u32_e32 v11, 0, v7
	v_max_i32_e32 v7, v7, v11
	v_cvt_f32_u32_e32 v11, v7
	v_sub_u32_e32 v12, 0, v7
	v_rcp_iflag_f32_e32 v11, v11
	s_nop 0
	v_mul_f32_e32 v11, 0x4f7ffffe, v11
	v_cvt_u32_f32_e32 v11, v11
	v_mul_lo_u32 v12, v12, v11
	v_mul_hi_u32 v12, v11, v12
	v_add_u32_e32 v11, v11, v12
	v_mul_hi_u32 v11, v6, v11
	v_mul_lo_u32 v11, v11, v7
	v_sub_u32_e32 v6, v6, v11
	v_sub_u32_e32 v11, v6, v7
	v_cmp_ge_u32_e32 vcc, v6, v7
	s_nop 1
	v_cndmask_b32_e32 v6, v6, v11, vcc
	v_sub_u32_e32 v11, v6, v7
	v_cmp_ge_u32_e32 vcc, v6, v7
	s_nop 1
	v_cndmask_b32_e32 v6, v6, v11, vcc
	v_xor_b32_e32 v6, v6, v10
	v_sub_u32_e32 v6, v6, v10
	v_add_u32_e32 v6, v9, v6
	v_lshl_or_b32 v6, v6, 8, v1
	v_ashrrev_i32_e32 v7, 31, v6
	v_lshlrev_b64 v[6:7], 6, v[6:7]
	v_lshl_add_u64 v[6:7], s[4:5], 0, v[6:7]
	global_load_dwordx4 v[42:45], v[6:7], off
	global_load_dwordx4 v[46:49], v[6:7], off offset:32
	global_load_dwordx4 v[50:53], v[6:7], off offset:16
	global_load_dwordx4 v[54:57], v[6:7], off offset:48
	v_cmp_le_i32_e32 vcc, s0, v0
	s_or_b64 s[6:7], vcc, s[6:7]
	s_andn2_b64 exec, exec, s[6:7]
	s_cbranch_execz .Lfrs_wait_p3
	s_mov_b64 s[22:23], exec
	v_ashrrev_i32_e32 v6, 8, v0
	v_mul_lo_u32 v6, v6, s66
	v_add_u32_e32 v7, s33, v6
	v_ashrrev_i32_e32 v6, 31, v7
	v_lshrrev_b32_e32 v6, 29, v6
	v_add_u32_e32 v9, v7, v6
	v_ashrrev_i32_e32 v6, 3, v9
	v_and_b32_e32 v9, -8, v9
	v_sub_u32_e32 v7, v7, v9
	v_cmp_gt_i32_e32 vcc, 0, v7
	v_add_u32_e32 v0, 0x200, v0
	s_nop 0
	v_cndmask_b32_e32 v9, v3, v4, vcc
	v_mad_u64_u32 v[6:7], s[12:13], v7, v9, v[6:7]
	v_mul_hi_i32 v7, v6, s1
	v_lshrrev_b32_e32 v9, 31, v7
	v_ashrrev_i32_e32 v7, 6, v7
	v_add_u32_e32 v7, v7, v9
	v_lshlrev_b32_e32 v9, 3, v7
	v_mul_lo_u32 v7, v7, s10
	v_sub_u32_e32 v10, 0x80, v9
	v_sub_u32_e32 v6, v6, v7
	v_min_i32_e32 v7, 8, v10
	v_sub_u32_e32 v11, 0, v6
	v_ashrrev_i32_e32 v10, 31, v6
	v_max_i32_e32 v6, v6, v11
	v_sub_u32_e32 v11, 0, v7
	v_max_i32_e32 v7, v7, v11
	v_cvt_f32_u32_e32 v11, v7
	v_sub_u32_e32 v12, 0, v7
	v_rcp_iflag_f32_e32 v11, v11
	s_nop 0
	v_mul_f32_e32 v11, 0x4f7ffffe, v11
	v_cvt_u32_f32_e32 v11, v11
	v_mul_lo_u32 v12, v12, v11
	v_mul_hi_u32 v12, v11, v12
	v_add_u32_e32 v11, v11, v12
	v_mul_hi_u32 v11, v6, v11
	v_mul_lo_u32 v11, v11, v7
	v_sub_u32_e32 v6, v6, v11
	v_sub_u32_e32 v11, v6, v7
	v_cmp_ge_u32_e32 vcc, v6, v7
	s_nop 1
	v_cndmask_b32_e32 v6, v6, v11, vcc
	v_sub_u32_e32 v11, v6, v7
	v_cmp_ge_u32_e32 vcc, v6, v7
	s_nop 1
	v_cndmask_b32_e32 v6, v6, v11, vcc
	v_xor_b32_e32 v6, v6, v10
	v_sub_u32_e32 v6, v6, v10
	v_add_u32_e32 v6, v9, v6
	v_lshl_or_b32 v6, v6, 8, v1
	v_ashrrev_i32_e32 v7, 31, v6
	v_lshlrev_b64 v[6:7], 6, v[6:7]
	v_lshl_add_u64 v[6:7], s[4:5], 0, v[6:7]
	global_load_dwordx4 v[58:61], v[6:7], off
	global_load_dwordx4 v[62:65], v[6:7], off offset:32
	global_load_dwordx4 v[66:69], v[6:7], off offset:16
	global_load_dwordx4 v[70:73], v[6:7], off offset:48
	v_cmp_le_i32_e32 vcc, s0, v0
	s_or_b64 s[6:7], vcc, s[6:7]
	s_andn2_b64 exec, exec, s[6:7]
	s_cbranch_execz .Lfrs_wait_p3
	s_mov_b64 s[24:25], exec
	v_ashrrev_i32_e32 v6, 8, v0
	v_mul_lo_u32 v6, v6, s66
	v_add_u32_e32 v7, s33, v6
	v_ashrrev_i32_e32 v6, 31, v7
	v_lshrrev_b32_e32 v6, 29, v6
	v_add_u32_e32 v9, v7, v6
	v_ashrrev_i32_e32 v6, 3, v9
	v_and_b32_e32 v9, -8, v9
	v_sub_u32_e32 v7, v7, v9
	v_cmp_gt_i32_e32 vcc, 0, v7
	v_add_u32_e32 v0, 0x200, v0
	s_nop 0
	v_cndmask_b32_e32 v9, v3, v4, vcc
	v_mad_u64_u32 v[6:7], s[12:13], v7, v9, v[6:7]
	v_mul_hi_i32 v7, v6, s1
	v_lshrrev_b32_e32 v9, 31, v7
	v_ashrrev_i32_e32 v7, 6, v7
	v_add_u32_e32 v7, v7, v9
	v_lshlrev_b32_e32 v9, 3, v7
	v_mul_lo_u32 v7, v7, s10
	v_sub_u32_e32 v10, 0x80, v9
	v_sub_u32_e32 v6, v6, v7
	v_min_i32_e32 v7, 8, v10
	v_sub_u32_e32 v11, 0, v6
	v_ashrrev_i32_e32 v10, 31, v6
	v_max_i32_e32 v6, v6, v11
	v_sub_u32_e32 v11, 0, v7
	v_max_i32_e32 v7, v7, v11
	v_cvt_f32_u32_e32 v11, v7
	v_sub_u32_e32 v12, 0, v7
	v_rcp_iflag_f32_e32 v11, v11
	s_nop 0
	v_mul_f32_e32 v11, 0x4f7ffffe, v11
	v_cvt_u32_f32_e32 v11, v11
	v_mul_lo_u32 v12, v12, v11
	v_mul_hi_u32 v12, v11, v12
	v_add_u32_e32 v11, v11, v12
	v_mul_hi_u32 v11, v6, v11
	v_mul_lo_u32 v11, v11, v7
	v_sub_u32_e32 v6, v6, v11
	v_sub_u32_e32 v11, v6, v7
	v_cmp_ge_u32_e32 vcc, v6, v7
	s_nop 1
	v_cndmask_b32_e32 v6, v6, v11, vcc
	v_sub_u32_e32 v11, v6, v7
	v_cmp_ge_u32_e32 vcc, v6, v7
	s_nop 1
	v_cndmask_b32_e32 v6, v6, v11, vcc
	v_xor_b32_e32 v6, v6, v10
	v_sub_u32_e32 v6, v6, v10
	v_add_u32_e32 v6, v9, v6
	v_lshl_or_b32 v6, v6, 8, v1
	v_ashrrev_i32_e32 v7, 31, v6
	v_lshlrev_b64 v[6:7], 6, v[6:7]
	v_lshl_add_u64 v[6:7], s[4:5], 0, v[6:7]
	global_load_dwordx4 v[74:77], v[6:7], off
	global_load_dwordx4 v[78:81], v[6:7], off offset:32
	global_load_dwordx4 v[82:85], v[6:7], off offset:16
	global_load_dwordx4 v[86:89], v[6:7], off offset:48
	v_cmp_le_i32_e32 vcc, s0, v0
	s_or_b64 s[6:7], vcc, s[6:7]
	s_andn2_b64 exec, exec, s[6:7]
	s_cbranch_execz .Lfrs_wait_p3
	s_mov_b64 s[26:27], exec
	v_ashrrev_i32_e32 v6, 8, v0
	v_mul_lo_u32 v6, v6, s66
	v_add_u32_e32 v7, s33, v6
	v_ashrrev_i32_e32 v6, 31, v7
	v_lshrrev_b32_e32 v6, 29, v6
	v_add_u32_e32 v9, v7, v6
	v_ashrrev_i32_e32 v6, 3, v9
	v_and_b32_e32 v9, -8, v9
	v_sub_u32_e32 v7, v7, v9
	v_cmp_gt_i32_e32 vcc, 0, v7
	v_add_u32_e32 v0, 0x200, v0
	s_nop 0
	v_cndmask_b32_e32 v9, v3, v4, vcc
	v_mad_u64_u32 v[6:7], s[12:13], v7, v9, v[6:7]
	v_mul_hi_i32 v7, v6, s1
	v_lshrrev_b32_e32 v9, 31, v7
	v_ashrrev_i32_e32 v7, 6, v7
	v_add_u32_e32 v7, v7, v9
	v_lshlrev_b32_e32 v9, 3, v7
	v_mul_lo_u32 v7, v7, s10
	v_sub_u32_e32 v10, 0x80, v9
	v_sub_u32_e32 v6, v6, v7
	v_min_i32_e32 v7, 8, v10
	v_sub_u32_e32 v11, 0, v6
	v_ashrrev_i32_e32 v10, 31, v6
	v_max_i32_e32 v6, v6, v11
	v_sub_u32_e32 v11, 0, v7
	v_max_i32_e32 v7, v7, v11
	v_cvt_f32_u32_e32 v11, v7
	v_sub_u32_e32 v12, 0, v7
	v_rcp_iflag_f32_e32 v11, v11
	s_nop 0
	v_mul_f32_e32 v11, 0x4f7ffffe, v11
	v_cvt_u32_f32_e32 v11, v11
	v_mul_lo_u32 v12, v12, v11
	v_mul_hi_u32 v12, v11, v12
	v_add_u32_e32 v11, v11, v12
	v_mul_hi_u32 v11, v6, v11
	v_mul_lo_u32 v11, v11, v7
	v_sub_u32_e32 v6, v6, v11
	v_sub_u32_e32 v11, v6, v7
	v_cmp_ge_u32_e32 vcc, v6, v7
	s_nop 1
	v_cndmask_b32_e32 v6, v6, v11, vcc
	v_sub_u32_e32 v11, v6, v7
	v_cmp_ge_u32_e32 vcc, v6, v7
	s_nop 1
	v_cndmask_b32_e32 v6, v6, v11, vcc
	v_xor_b32_e32 v6, v6, v10
	v_sub_u32_e32 v6, v6, v10
	v_add_u32_e32 v6, v9, v6
	v_lshl_or_b32 v6, v6, 8, v1
	v_ashrrev_i32_e32 v7, 31, v6
	v_lshlrev_b64 v[6:7], 6, v[6:7]
	v_lshl_add_u64 v[6:7], s[4:5], 0, v[6:7]
	global_load_dwordx4 v[90:93], v[6:7], off
	global_load_dwordx4 v[94:97], v[6:7], off offset:32
	global_load_dwordx4 v[98:101], v[6:7], off offset:16
	global_load_dwordx4 v[102:105], v[6:7], off offset:48
	v_cmp_le_i32_e32 vcc, s0, v0
	s_or_b64 s[6:7], vcc, s[6:7]
	s_andn2_b64 exec, exec, s[6:7]
	s_cbranch_execz .Lfrs_wait_p3
	s_mov_b64 s[98:99], exec
	v_ashrrev_i32_e32 v6, 8, v0
	v_mul_lo_u32 v6, v6, s66
	v_add_u32_e32 v7, s33, v6
	v_ashrrev_i32_e32 v6, 31, v7
	v_lshrrev_b32_e32 v6, 29, v6
	v_add_u32_e32 v9, v7, v6
	v_ashrrev_i32_e32 v6, 3, v9
	v_and_b32_e32 v9, -8, v9
	v_sub_u32_e32 v7, v7, v9
	v_cmp_gt_i32_e32 vcc, 0, v7
	v_add_u32_e32 v0, 0x200, v0
	s_nop 0
	v_cndmask_b32_e32 v9, v3, v4, vcc
	v_mad_u64_u32 v[6:7], s[12:13], v7, v9, v[6:7]
	v_mul_hi_i32 v7, v6, s1
	v_lshrrev_b32_e32 v9, 31, v7
	v_ashrrev_i32_e32 v7, 6, v7
	v_add_u32_e32 v7, v7, v9
	v_lshlrev_b32_e32 v9, 3, v7
	v_mul_lo_u32 v7, v7, s10
	v_sub_u32_e32 v10, 0x80, v9
	v_sub_u32_e32 v6, v6, v7
	v_min_i32_e32 v7, 8, v10
	v_sub_u32_e32 v11, 0, v6
	v_ashrrev_i32_e32 v10, 31, v6
	v_max_i32_e32 v6, v6, v11
	v_sub_u32_e32 v11, 0, v7
	v_max_i32_e32 v7, v7, v11
	v_cvt_f32_u32_e32 v11, v7
	v_sub_u32_e32 v12, 0, v7
	v_rcp_iflag_f32_e32 v11, v11
	s_nop 0
	v_mul_f32_e32 v11, 0x4f7ffffe, v11
	v_cvt_u32_f32_e32 v11, v11
	v_mul_lo_u32 v12, v12, v11
	v_mul_hi_u32 v12, v11, v12
	v_add_u32_e32 v11, v11, v12
	v_mul_hi_u32 v11, v6, v11
	v_mul_lo_u32 v11, v11, v7
	v_sub_u32_e32 v6, v6, v11
	v_sub_u32_e32 v11, v6, v7
	v_cmp_ge_u32_e32 vcc, v6, v7
	s_nop 1
	v_cndmask_b32_e32 v6, v6, v11, vcc
	v_sub_u32_e32 v11, v6, v7
	v_cmp_ge_u32_e32 vcc, v6, v7
	s_nop 1
	v_cndmask_b32_e32 v6, v6, v11, vcc
	v_xor_b32_e32 v6, v6, v10
	v_sub_u32_e32 v6, v6, v10
	v_add_u32_e32 v6, v9, v6
	v_lshl_or_b32 v6, v6, 8, v1
	v_ashrrev_i32_e32 v7, 31, v6
	v_lshlrev_b64 v[6:7], 6, v[6:7]
	v_lshl_add_u64 v[6:7], s[4:5], 0, v[6:7]
	global_load_dwordx4 v[106:109], v[6:7], off
	global_load_dwordx4 v[110:113], v[6:7], off offset:32
	global_load_dwordx4 v[114:117], v[6:7], off offset:16
	global_load_dwordx4 v[118:121], v[6:7], off offset:48
	v_cmp_le_i32_e32 vcc, s0, v0
	s_or_b64 s[6:7], vcc, s[6:7]
	s_andn2_b64 exec, exec, s[6:7]
.Lfrs_wait_p3:
	s_mov_b64 s[100:101], exec
	s_waitcnt vmcnt(0)
	s_mov_b64 exec, s[14:15]
	v_mov_b32_e32 v6, v26
	v_mov_b32_e32 v7, v30
	v_mov_b32_e32 v30, v27
	v_mov_b32_e32 v26, v28
	v_mov_b32_e32 v27, v32
	v_mov_b32_e32 v32, v29
	v_mov_b32_e32 v28, v34
	v_mov_b32_e32 v29, v38
	v_mov_b32_e32 v38, v35
	v_mov_b32_e32 v34, v36
	v_mov_b32_e32 v35, v40
	v_mov_b32_e32 v40, v37
	v_pk_add_f32 v[6:7], v[6:7], v[30:31]
	v_pk_add_f32 v[26:27], v[26:27], v[32:33]
	v_pk_add_f32 v[28:29], v[28:29], v[38:39]
	v_pk_add_f32 v[30:31], v[34:35], v[40:41]
	v_pk_add_f32 v[6:7], v[6:7], v[26:27]
	v_pk_add_f32 v[26:27], v[28:29], v[30:31]
	s_nop 0
	v_pk_add_f32 v[6:7], v[6:7], v[26:27]
	s_nop 0
	v_add_f32_e32 v6, v6, v7
	v_fmamk_f32 v6, v6, 0x3a800000, v5
	v_rsq_f32_e32 v6, v6
	ds_write_b32 v122, v6
	v_add_u32_e32 v122, 0x800, v122
	s_mov_b64 exec, s[16:17]
	v_mov_b32_e32 v6, v42
	v_mov_b32_e32 v7, v46
	v_mov_b32_e32 v46, v43
	v_mov_b32_e32 v42, v44
	v_mov_b32_e32 v43, v48
	v_mov_b32_e32 v48, v45
	v_mov_b32_e32 v44, v50
	v_mov_b32_e32 v45, v54
	v_mov_b32_e32 v54, v51
	v_mov_b32_e32 v50, v52
	v_mov_b32_e32 v51, v56
	v_mov_b32_e32 v56, v53
	v_pk_add_f32 v[6:7], v[6:7], v[46:47]
	v_pk_add_f32 v[42:43], v[42:43], v[48:49]
	v_pk_add_f32 v[44:45], v[44:45], v[54:55]
	v_pk_add_f32 v[46:47], v[50:51], v[56:57]
	v_pk_add_f32 v[6:7], v[6:7], v[42:43]
	v_pk_add_f32 v[42:43], v[44:45], v[46:47]
	s_nop 0
	v_pk_add_f32 v[6:7], v[6:7], v[42:43]
	s_nop 0
	v_add_f32_e32 v6, v6, v7
	v_fmamk_f32 v6, v6, 0x3a800000, v5
	v_rsq_f32_e32 v6, v6
	ds_write_b32 v122, v6
	v_add_u32_e32 v122, 0x800, v122
	s_mov_b64 exec, s[22:23]
	v_mov_b32_e32 v6, v58
	v_mov_b32_e32 v7, v62
	v_mov_b32_e32 v62, v59
	v_mov_b32_e32 v58, v60
	v_mov_b32_e32 v59, v64
	v_mov_b32_e32 v64, v61
	v_mov_b32_e32 v60, v66
	v_mov_b32_e32 v61, v70
	v_mov_b32_e32 v70, v67
	v_mov_b32_e32 v66, v68
	v_mov_b32_e32 v67, v72
	v_mov_b32_e32 v72, v69
	v_pk_add_f32 v[6:7], v[6:7], v[62:63]
	v_pk_add_f32 v[58:59], v[58:59], v[64:65]
	v_pk_add_f32 v[60:61], v[60:61], v[70:71]
	v_pk_add_f32 v[62:63], v[66:67], v[72:73]
	v_pk_add_f32 v[6:7], v[6:7], v[58:59]
	v_pk_add_f32 v[58:59], v[60:61], v[62:63]
	s_nop 0
	v_pk_add_f32 v[6:7], v[6:7], v[58:59]
	s_nop 0
	v_add_f32_e32 v6, v6, v7
	v_fmamk_f32 v6, v6, 0x3a800000, v5
	v_rsq_f32_e32 v6, v6
	ds_write_b32 v122, v6
	v_add_u32_e32 v122, 0x800, v122
	s_mov_b64 exec, s[24:25]
	v_mov_b32_e32 v6, v74
	v_mov_b32_e32 v7, v78
	v_mov_b32_e32 v78, v75
	v_mov_b32_e32 v74, v76
	v_mov_b32_e32 v75, v80
	v_mov_b32_e32 v80, v77
	v_mov_b32_e32 v76, v82
	v_mov_b32_e32 v77, v86
	v_mov_b32_e32 v86, v83
	v_mov_b32_e32 v82, v84
	v_mov_b32_e32 v83, v88
	v_mov_b32_e32 v88, v85
	v_pk_add_f32 v[6:7], v[6:7], v[78:79]
	v_pk_add_f32 v[74:75], v[74:75], v[80:81]
	v_pk_add_f32 v[76:77], v[76:77], v[86:87]
	v_pk_add_f32 v[78:79], v[82:83], v[88:89]
	v_pk_add_f32 v[6:7], v[6:7], v[74:75]
	v_pk_add_f32 v[74:75], v[76:77], v[78:79]
	s_nop 0
	v_pk_add_f32 v[6:7], v[6:7], v[74:75]
	s_nop 0
	v_add_f32_e32 v6, v6, v7
	v_fmamk_f32 v6, v6, 0x3a800000, v5
	v_rsq_f32_e32 v6, v6
	ds_write_b32 v122, v6
	v_add_u32_e32 v122, 0x800, v122
	s_mov_b64 exec, s[26:27]
	v_mov_b32_e32 v6, v90
	v_mov_b32_e32 v7, v94
	v_mov_b32_e32 v94, v91
	v_mov_b32_e32 v90, v92
	v_mov_b32_e32 v91, v96
	v_mov_b32_e32 v96, v93
	v_mov_b32_e32 v92, v98
	v_mov_b32_e32 v93, v102
	v_mov_b32_e32 v102, v99
	v_mov_b32_e32 v98, v100
	v_mov_b32_e32 v99, v104
	v_mov_b32_e32 v104, v101
	v_pk_add_f32 v[6:7], v[6:7], v[94:95]
	v_pk_add_f32 v[90:91], v[90:91], v[96:97]
	v_pk_add_f32 v[92:93], v[92:93], v[102:103]
	v_pk_add_f32 v[94:95], v[98:99], v[104:105]
	v_pk_add_f32 v[6:7], v[6:7], v[90:91]
	v_pk_add_f32 v[90:91], v[92:93], v[94:95]
	s_nop 0
	v_pk_add_f32 v[6:7], v[6:7], v[90:91]
	s_nop 0
	v_add_f32_e32 v6, v6, v7
	v_fmamk_f32 v6, v6, 0x3a800000, v5
	v_rsq_f32_e32 v6, v6
	ds_write_b32 v122, v6
	v_add_u32_e32 v122, 0x800, v122
	s_mov_b64 exec, s[98:99]
	v_mov_b32_e32 v6, v106
	v_mov_b32_e32 v7, v110
	v_mov_b32_e32 v110, v107
	v_mov_b32_e32 v106, v108
	v_mov_b32_e32 v107, v112
	v_mov_b32_e32 v112, v109
	v_mov_b32_e32 v108, v114
	v_mov_b32_e32 v109, v118
	v_mov_b32_e32 v118, v115
	v_mov_b32_e32 v114, v116
	v_mov_b32_e32 v115, v120
	v_mov_b32_e32 v120, v117
	v_pk_add_f32 v[6:7], v[6:7], v[110:111]
	v_pk_add_f32 v[106:107], v[106:107], v[112:113]
	v_pk_add_f32 v[108:109], v[108:109], v[118:119]
	v_pk_add_f32 v[110:111], v[114:115], v[120:121]
	v_pk_add_f32 v[6:7], v[6:7], v[106:107]
	v_pk_add_f32 v[106:107], v[108:109], v[110:111]
	s_nop 0
	v_pk_add_f32 v[6:7], v[6:7], v[106:107]
	s_nop 0
	v_add_f32_e32 v6, v6, v7
	v_fmamk_f32 v6, v6, 0x3a800000, v5
	v_rsq_f32_e32 v6, v6
	ds_write_b32 v122, v6
	v_add_u32_e32 v122, 0x800, v122
	s_mov_b64 exec, s[100:101]
	v_add_u32_e32 v2, 0x3000, v2
	s_cbranch_execz .LBB0_553

.LBB0_1225:
	s_cmp_lt_i32 s42, 10
	s_cselect_b64 s[0:1], -1, 0
	s_and_b64 s[4:5], s[0:1], s[2:3]
	s_andn2_b64 vcc, exec, s[4:5]
	s_cbranch_vccnz .LBB0_1245
	v_mbcnt_hi_u32_b32 v0, -1, v230
	v_readlane_b32 s0, v248, 0
	s_sub_i32 s1, s66, s33
	s_add_i32 s2, s1, 0xaff
	v_add_u32_e32 v8, s0, v0
	s_abs_i32 s0, s66
	s_waitcnt lgkmcnt(0)
	v_cvt_f32_u32_e32 v1, s0
	s_sub_i32 s1, 0xfffff501, s1
	s_xor_b32 s3, s2, s66
	s_max_i32 s1, s2, s1
	v_rcp_iflag_f32_e32 v1, v1
	s_sub_i32 s2, 0, s0
	s_ashr_i32 s3, s3, 31
	v_mov_b32_e32 v0, v8
	v_mul_f32_e32 v1, 0x4f7ffffe, v1
	v_cvt_u32_f32_e32 v1, v1
	s_nop 0
	v_readfirstlane_b32 s6, v1
	s_mul_i32 s2, s2, s6
	s_mul_hi_u32 s2, s6, s2
	s_add_i32 s6, s6, s2
	s_mul_hi_u32 s2, s1, s6
	s_mul_i32 s6, s2, s0
	s_sub_i32 s1, s1, s6
	s_add_i32 s6, s2, 1
	s_sub_i32 s7, s1, s0
	s_cmp_ge_u32 s1, s0
	s_cselect_b32 s2, s6, s2
	s_cselect_b32 s1, s7, s1
	s_add_i32 s6, s2, 1
	s_cmp_ge_u32 s1, s0
	s_cselect_b32 s0, s6, s2
	s_xor_b32 s0, s0, s3
	s_sub_i32 s0, s0, s3
	s_lshl_b32 s0, s0, 8
	v_cmp_gt_i32_e32 vcc, s0, v0
	s_and_saveexec_b64 s[2:3], vcc
	s_cbranch_execz .LBB0_1229
	s_add_u32 s6, s40, 0x3400000
	v_lshl_add_u32 v2, v0, 2, 0
	s_addc_u32 s7, s41, 0
	v_and_b32_e32 v1, 0xff, v0
	v_add_u32_e32 v2, 0x20100, v2
	s_mov_b64 s[8:9], 0
	v_mov_b32_e32 v3, 0x160
	v_mov_b32_e32 v4, 0x161
	s_mov_b32 s1, 0x2e8ba2e9
	s_movk_i32 s10, 0xb0
	v_mov_b32_e32 v5, 0x358637bd
	s_mov_b64 s[14:15], 0
	s_mov_b64 s[16:17], 0
	s_mov_b64 s[22:23], 0
	s_mov_b64 s[24:25], 0
	s_mov_b64 s[26:27], 0
	s_mov_b64 s[98:99], 0
	v_mov_b32_e32 v122, v2
	s_mov_b64 s[14:15], exec
	v_ashrrev_i32_e32 v6, 8, v0
	v_mul_lo_u32 v6, v6, s66
	v_add_u32_e32 v7, s33, v6
	v_ashrrev_i32_e32 v6, 31, v7
	v_lshrrev_b32_e32 v6, 29, v6
	v_add_u32_e32 v9, v7, v6
	v_ashrrev_i32_e32 v6, 3, v9
	v_and_b32_e32 v9, -8, v9
	v_sub_u32_e32 v7, v7, v9
	v_cmp_gt_i32_e32 vcc, 0, v7
	v_add_u32_e32 v0, 0x200, v0
	s_nop 0
	v_cndmask_b32_e32 v9, v3, v4, vcc
	v_mad_u64_u32 v[6:7], s[12:13], v7, v9, v[6:7]
	v_mul_hi_i32 v7, v6, s1
	v_lshrrev_b32_e32 v9, 31, v7
	v_ashrrev_i32_e32 v7, 5, v7
	v_add_u32_e32 v7, v7, v9
	v_lshlrev_b32_e32 v9, 3, v7
	v_mul_lo_u32 v7, v7, s10
	v_sub_u32_e32 v10, 0x80, v9
	v_sub_u32_e32 v6, v6, v7
	v_min_i32_e32 v7, 8, v10
	v_sub_u32_e32 v11, 0, v6
	v_ashrrev_i32_e32 v10, 31, v6
	v_max_i32_e32 v6, v6, v11
	v_sub_u32_e32 v11, 0, v7
	v_max_i32_e32 v7, v7, v11
	v_cvt_f32_u32_e32 v11, v7
	v_sub_u32_e32 v12, 0, v7
	v_rcp_iflag_f32_e32 v11, v11
	s_nop 0
	v_mul_f32_e32 v11, 0x4f7ffffe, v11
	v_cvt_u32_f32_e32 v11, v11
	v_mul_lo_u32 v12, v12, v11
	v_mul_hi_u32 v12, v11, v12
	v_add_u32_e32 v11, v11, v12
	v_mul_hi_u32 v11, v6, v11
	v_mul_lo_u32 v11, v11, v7
	v_sub_u32_e32 v6, v6, v11
	v_sub_u32_e32 v11, v6, v7
	v_cmp_ge_u32_e32 vcc, v6, v7
	s_nop 1
	v_cndmask_b32_e32 v6, v6, v11, vcc
	v_sub_u32_e32 v11, v6, v7
	v_cmp_ge_u32_e32 vcc, v6, v7
	s_nop 1
	v_cndmask_b32_e32 v6, v6, v11, vcc
	v_xor_b32_e32 v6, v6, v10
	v_sub_u32_e32 v6, v6, v10
	v_add_u32_e32 v6, v9, v6
	v_lshl_or_b32 v6, v6, 8, v1
	v_ashrrev_i32_e32 v7, 31, v6
	v_lshlrev_b64 v[6:7], 6, v[6:7]
	v_lshl_add_u64 v[6:7], s[6:7], 0, v[6:7]
	global_load_dwordx4 v[26:29], v[6:7], off
	global_load_dwordx4 v[30:33], v[6:7], off offset:32
	global_load_dwordx4 v[34:37], v[6:7], off offset:16
	global_load_dwordx4 v[38:41], v[6:7], off offset:48
	v_cmp_le_i32_e32 vcc, s0, v0
	s_or_b64 s[8:9], vcc, s[8:9]
	s_andn2_b64 exec, exec, s[8:9]
	s_cbranch_execz .Lfrs_wait_p9
	s_mov_b64 s[16:17], exec
	v_ashrrev_i32_e32 v6, 8, v0
	v_mul_lo_u32 v6, v6, s66
	v_add_u32_e32 v7, s33, v6
	v_ashrrev_i32_e32 v6, 31, v7
	v_lshrrev_b32_e32 v6, 29, v6
	v_add_u32_e32 v9, v7, v6
	v_ashrrev_i32_e32 v6, 3, v9
	v_and_b32_e32 v9, -8, v9
	v_sub_u32_e32 v7, v7, v9
	v_cmp_gt_i32_e32 vcc, 0, v7
	v_add_u32_e32 v0, 0x200, v0
	s_nop 0
	v_cndmask_b32_e32 v9, v3, v4, vcc
	v_mad_u64_u32 v[6:7], s[12:13], v7, v9, v[6:7]
	v_mul_hi_i32 v7, v6, s1
	v_lshrrev_b32_e32 v9, 31, v7
	v_ashrrev_i32_e32 v7, 5, v7
	v_add_u32_e32 v7, v7, v9
	v_lshlrev_b32_e32 v9, 3, v7
	v_mul_lo_u32 v7, v7, s10
	v_sub_u32_e32 v10, 0x80, v9
	v_sub_u32_e32 v6, v6, v7
	v_min_i32_e32 v7, 8, v10
	v_sub_u32_e32 v11, 0, v6
	v_ashrrev_i32_e32 v10, 31, v6
	v_max_i32_e32 v6, v6, v11
	v_sub_u32_e32 v11, 0, v7
	v_max_i32_e32 v7, v7, v11
	v_cvt_f32_u32_e32 v11, v7
	v_sub_u32_e32 v12, 0, v7
	v_rcp_iflag_f32_e32 v11, v11
	s_nop 0
	v_mul_f32_e32 v11, 0x4f7ffffe, v11
	v_cvt_u32_f32_e32 v11, v11
	v_mul_lo_u32 v12, v12, v11
	v_mul_hi_u32 v12, v11, v12
	v_add_u32_e32 v11, v11, v12
	v_mul_hi_u32 v11, v6, v11
	v_mul_lo_u32 v11, v11, v7
	v_sub_u32_e32 v6, v6, v11
	v_sub_u32_e32 v11, v6, v7
	v_cmp_ge_u32_e32 vcc, v6, v7
	s_nop 1
	v_cndmask_b32_e32 v6, v6, v11, vcc
	v_sub_u32_e32 v11, v6, v7
	v_cmp_ge_u32_e32 vcc, v6, v7
	s_nop 1
	v_cndmask_b32_e32 v6, v6, v11, vcc
	v_xor_b32_e32 v6, v6, v10
	v_sub_u32_e32 v6, v6, v10
	v_add_u32_e32 v6, v9, v6
	v_lshl_or_b32 v6, v6, 8, v1
	v_ashrrev_i32_e32 v7, 31, v6
	v_lshlrev_b64 v[6:7], 6, v[6:7]
	v_lshl_add_u64 v[6:7], s[6:7], 0, v[6:7]
	global_load_dwordx4 v[42:45], v[6:7], off
	global_load_dwordx4 v[46:49], v[6:7], off offset:32
	global_load_dwordx4 v[50:53], v[6:7], off offset:16
	global_load_dwordx4 v[54:57], v[6:7], off offset:48
	v_cmp_le_i32_e32 vcc, s0, v0
	s_or_b64 s[8:9], vcc, s[8:9]
	s_andn2_b64 exec, exec, s[8:9]
	s_cbranch_execz .Lfrs_wait_p9
	s_mov_b64 s[22:23], exec
	v_ashrrev_i32_e32 v6, 8, v0
	v_mul_lo_u32 v6, v6, s66
	v_add_u32_e32 v7, s33, v6
	v_ashrrev_i32_e32 v6, 31, v7
	v_lshrrev_b32_e32 v6, 29, v6
	v_add_u32_e32 v9, v7, v6
	v_ashrrev_i32_e32 v6, 3, v9
	v_and_b32_e32 v9, -8, v9
	v_sub_u32_e32 v7, v7, v9
	v_cmp_gt_i32_e32 vcc, 0, v7
	v_add_u32_e32 v0, 0x200, v0
	s_nop 0
	v_cndmask_b32_e32 v9, v3, v4, vcc
	v_mad_u64_u32 v[6:7], s[12:13], v7, v9, v[6:7]
	v_mul_hi_i32 v7, v6, s1
	v_lshrrev_b32_e32 v9, 31, v7
	v_ashrrev_i32_e32 v7, 5, v7
	v_add_u32_e32 v7, v7, v9
	v_lshlrev_b32_e32 v9, 3, v7
	v_mul_lo_u32 v7, v7, s10
	v_sub_u32_e32 v10, 0x80, v9
	v_sub_u32_e32 v6, v6, v7
	v_min_i32_e32 v7, 8, v10
	v_sub_u32_e32 v11, 0, v6
	v_ashrrev_i32_e32 v10, 31, v6
	v_max_i32_e32 v6, v6, v11
	v_sub_u32_e32 v11, 0, v7
	v_max_i32_e32 v7, v7, v11
	v_cvt_f32_u32_e32 v11, v7
	v_sub_u32_e32 v12, 0, v7
	v_rcp_iflag_f32_e32 v11, v11
	s_nop 0
	v_mul_f32_e32 v11, 0x4f7ffffe, v11
	v_cvt_u32_f32_e32 v11, v11
	v_mul_lo_u32 v12, v12, v11
	v_mul_hi_u32 v12, v11, v12
	v_add_u32_e32 v11, v11, v12
	v_mul_hi_u32 v11, v6, v11
	v_mul_lo_u32 v11, v11, v7
	v_sub_u32_e32 v6, v6, v11
	v_sub_u32_e32 v11, v6, v7
	v_cmp_ge_u32_e32 vcc, v6, v7
	s_nop 1
	v_cndmask_b32_e32 v6, v6, v11, vcc
	v_sub_u32_e32 v11, v6, v7
	v_cmp_ge_u32_e32 vcc, v6, v7
	s_nop 1
	v_cndmask_b32_e32 v6, v6, v11, vcc
	v_xor_b32_e32 v6, v6, v10
	v_sub_u32_e32 v6, v6, v10
	v_add_u32_e32 v6, v9, v6
	v_lshl_or_b32 v6, v6, 8, v1
	v_ashrrev_i32_e32 v7, 31, v6
	v_lshlrev_b64 v[6:7], 6, v[6:7]
	v_lshl_add_u64 v[6:7], s[6:7], 0, v[6:7]
	global_load_dwordx4 v[58:61], v[6:7], off
	global_load_dwordx4 v[62:65], v[6:7], off offset:32
	global_load_dwordx4 v[66:69], v[6:7], off offset:16
	global_load_dwordx4 v[70:73], v[6:7], off offset:48
	v_cmp_le_i32_e32 vcc, s0, v0
	s_or_b64 s[8:9], vcc, s[8:9]
	s_andn2_b64 exec, exec, s[8:9]
	s_cbranch_execz .Lfrs_wait_p9
	s_mov_b64 s[24:25], exec
	v_ashrrev_i32_e32 v6, 8, v0
	v_mul_lo_u32 v6, v6, s66
	v_add_u32_e32 v7, s33, v6
	v_ashrrev_i32_e32 v6, 31, v7
	v_lshrrev_b32_e32 v6, 29, v6
	v_add_u32_e32 v9, v7, v6
	v_ashrrev_i32_e32 v6, 3, v9
	v_and_b32_e32 v9, -8, v9
	v_sub_u32_e32 v7, v7, v9
	v_cmp_gt_i32_e32 vcc, 0, v7
	v_add_u32_e32 v0, 0x200, v0
	s_nop 0
	v_cndmask_b32_e32 v9, v3, v4, vcc
	v_mad_u64_u32 v[6:7], s[12:13], v7, v9, v[6:7]
	v_mul_hi_i32 v7, v6, s1
	v_lshrrev_b32_e32 v9, 31, v7
	v_ashrrev_i32_e32 v7, 5, v7
	v_add_u32_e32 v7, v7, v9
	v_lshlrev_b32_e32 v9, 3, v7
	v_mul_lo_u32 v7, v7, s10
	v_sub_u32_e32 v10, 0x80, v9
	v_sub_u32_e32 v6, v6, v7
	v_min_i32_e32 v7, 8, v10
	v_sub_u32_e32 v11, 0, v6
	v_ashrrev_i32_e32 v10, 31, v6
	v_max_i32_e32 v6, v6, v11
	v_sub_u32_e32 v11, 0, v7
	v_max_i32_e32 v7, v7, v11
	v_cvt_f32_u32_e32 v11, v7
	v_sub_u32_e32 v12, 0, v7
	v_rcp_iflag_f32_e32 v11, v11
	s_nop 0
	v_mul_f32_e32 v11, 0x4f7ffffe, v11
	v_cvt_u32_f32_e32 v11, v11
	v_mul_lo_u32 v12, v12, v11
	v_mul_hi_u32 v12, v11, v12
	v_add_u32_e32 v11, v11, v12
	v_mul_hi_u32 v11, v6, v11
	v_mul_lo_u32 v11, v11, v7
	v_sub_u32_e32 v6, v6, v11
	v_sub_u32_e32 v11, v6, v7
	v_cmp_ge_u32_e32 vcc, v6, v7
	s_nop 1
	v_cndmask_b32_e32 v6, v6, v11, vcc
	v_sub_u32_e32 v11, v6, v7
	v_cmp_ge_u32_e32 vcc, v6, v7
	s_nop 1
	v_cndmask_b32_e32 v6, v6, v11, vcc
	v_xor_b32_e32 v6, v6, v10
	v_sub_u32_e32 v6, v6, v10
	v_add_u32_e32 v6, v9, v6
	v_lshl_or_b32 v6, v6, 8, v1
	v_ashrrev_i32_e32 v7, 31, v6
	v_lshlrev_b64 v[6:7], 6, v[6:7]
	v_lshl_add_u64 v[6:7], s[6:7], 0, v[6:7]
	global_load_dwordx4 v[74:77], v[6:7], off
	global_load_dwordx4 v[78:81], v[6:7], off offset:32
	global_load_dwordx4 v[82:85], v[6:7], off offset:16
	global_load_dwordx4 v[86:89], v[6:7], off offset:48
	v_cmp_le_i32_e32 vcc, s0, v0
	s_or_b64 s[8:9], vcc, s[8:9]
	s_andn2_b64 exec, exec, s[8:9]
	s_cbranch_execz .Lfrs_wait_p9
	s_mov_b64 s[26:27], exec
	v_ashrrev_i32_e32 v6, 8, v0
	v_mul_lo_u32 v6, v6, s66
	v_add_u32_e32 v7, s33, v6
	v_ashrrev_i32_e32 v6, 31, v7
	v_lshrrev_b32_e32 v6, 29, v6
	v_add_u32_e32 v9, v7, v6
	v_ashrrev_i32_e32 v6, 3, v9
	v_and_b32_e32 v9, -8, v9
	v_sub_u32_e32 v7, v7, v9
	v_cmp_gt_i32_e32 vcc, 0, v7
	v_add_u32_e32 v0, 0x200, v0
	s_nop 0
	v_cndmask_b32_e32 v9, v3, v4, vcc
	v_mad_u64_u32 v[6:7], s[12:13], v7, v9, v[6:7]
	v_mul_hi_i32 v7, v6, s1
	v_lshrrev_b32_e32 v9, 31, v7
	v_ashrrev_i32_e32 v7, 5, v7
	v_add_u32_e32 v7, v7, v9
	v_lshlrev_b32_e32 v9, 3, v7
	v_mul_lo_u32 v7, v7, s10
	v_sub_u32_e32 v10, 0x80, v9
	v_sub_u32_e32 v6, v6, v7
	v_min_i32_e32 v7, 8, v10
	v_sub_u32_e32 v11, 0, v6
	v_ashrrev_i32_e32 v10, 31, v6
	v_max_i32_e32 v6, v6, v11
	v_sub_u32_e32 v11, 0, v7
	v_max_i32_e32 v7, v7, v11
	v_cvt_f32_u32_e32 v11, v7
	v_sub_u32_e32 v12, 0, v7
	v_rcp_iflag_f32_e32 v11, v11
	s_nop 0
	v_mul_f32_e32 v11, 0x4f7ffffe, v11
	v_cvt_u32_f32_e32 v11, v11
	v_mul_lo_u32 v12, v12, v11
	v_mul_hi_u32 v12, v11, v12
	v_add_u32_e32 v11, v11, v12
	v_mul_hi_u32 v11, v6, v11
	v_mul_lo_u32 v11, v11, v7
	v_sub_u32_e32 v6, v6, v11
	v_sub_u32_e32 v11, v6, v7
	v_cmp_ge_u32_e32 vcc, v6, v7
	s_nop 1
	v_cndmask_b32_e32 v6, v6, v11, vcc
	v_sub_u32_e32 v11, v6, v7
	v_cmp_ge_u32_e32 vcc, v6, v7
	s_nop 1
	v_cndmask_b32_e32 v6, v6, v11, vcc
	v_xor_b32_e32 v6, v6, v10
	v_sub_u32_e32 v6, v6, v10
	v_add_u32_e32 v6, v9, v6
	v_lshl_or_b32 v6, v6, 8, v1
	v_ashrrev_i32_e32 v7, 31, v6
	v_lshlrev_b64 v[6:7], 6, v[6:7]
	v_lshl_add_u64 v[6:7], s[6:7], 0, v[6:7]
	global_load_dwordx4 v[90:93], v[6:7], off
	global_load_dwordx4 v[94:97], v[6:7], off offset:32
	global_load_dwordx4 v[98:101], v[6:7], off offset:16
	global_load_dwordx4 v[102:105], v[6:7], off offset:48
	v_cmp_le_i32_e32 vcc, s0, v0
	s_or_b64 s[8:9], vcc, s[8:9]
	s_andn2_b64 exec, exec, s[8:9]
	s_cbranch_execz .Lfrs_wait_p9
	s_mov_b64 s[98:99], exec
	v_ashrrev_i32_e32 v6, 8, v0
	v_mul_lo_u32 v6, v6, s66
	v_add_u32_e32 v7, s33, v6
	v_ashrrev_i32_e32 v6, 31, v7
	v_lshrrev_b32_e32 v6, 29, v6
	v_add_u32_e32 v9, v7, v6
	v_ashrrev_i32_e32 v6, 3, v9
	v_and_b32_e32 v9, -8, v9
	v_sub_u32_e32 v7, v7, v9
	v_cmp_gt_i32_e32 vcc, 0, v7
	v_add_u32_e32 v0, 0x200, v0
	s_nop 0
	v_cndmask_b32_e32 v9, v3, v4, vcc
	v_mad_u64_u32 v[6:7], s[12:13], v7, v9, v[6:7]
	v_mul_hi_i32 v7, v6, s1
	v_lshrrev_b32_e32 v9, 31, v7
	v_ashrrev_i32_e32 v7, 5, v7
	v_add_u32_e32 v7, v7, v9
	v_lshlrev_b32_e32 v9, 3, v7
	v_mul_lo_u32 v7, v7, s10
	v_sub_u32_e32 v10, 0x80, v9
	v_sub_u32_e32 v6, v6, v7
	v_min_i32_e32 v7, 8, v10
	v_sub_u32_e32 v11, 0, v6
	v_ashrrev_i32_e32 v10, 31, v6
	v_max_i32_e32 v6, v6, v11
	v_sub_u32_e32 v11, 0, v7
	v_max_i32_e32 v7, v7, v11
	v_cvt_f32_u32_e32 v11, v7
	v_sub_u32_e32 v12, 0, v7
	v_rcp_iflag_f32_e32 v11, v11
	s_nop 0
	v_mul_f32_e32 v11, 0x4f7ffffe, v11
	v_cvt_u32_f32_e32 v11, v11
	v_mul_lo_u32 v12, v12, v11
	v_mul_hi_u32 v12, v11, v12
	v_add_u32_e32 v11, v11, v12
	v_mul_hi_u32 v11, v6, v11
	v_mul_lo_u32 v11, v11, v7
	v_sub_u32_e32 v6, v6, v11
	v_sub_u32_e32 v11, v6, v7
	v_cmp_ge_u32_e32 vcc, v6, v7
	s_nop 1
	v_cndmask_b32_e32 v6, v6, v11, vcc
	v_sub_u32_e32 v11, v6, v7
	v_cmp_ge_u32_e32 vcc, v6, v7
	s_nop 1
	v_cndmask_b32_e32 v6, v6, v11, vcc
	v_xor_b32_e32 v6, v6, v10
	v_sub_u32_e32 v6, v6, v10
	v_add_u32_e32 v6, v9, v6
	v_lshl_or_b32 v6, v6, 8, v1
	v_ashrrev_i32_e32 v7, 31, v6
	v_lshlrev_b64 v[6:7], 6, v[6:7]
	v_lshl_add_u64 v[6:7], s[6:7], 0, v[6:7]
	global_load_dwordx4 v[106:109], v[6:7], off
	global_load_dwordx4 v[110:113], v[6:7], off offset:32
	global_load_dwordx4 v[114:117], v[6:7], off offset:16
	global_load_dwordx4 v[118:121], v[6:7], off offset:48
	v_cmp_le_i32_e32 vcc, s0, v0
	s_or_b64 s[8:9], vcc, s[8:9]
	s_andn2_b64 exec, exec, s[8:9]
